# one static priority raise for waves 4-7 during the stick-breaking attention phase
# speedup vs baseline: 1.0029x; 1.0029x over previous
; #define LAS __attribute__((address_space(3)))
; DI int launder(int x) { asm volatile("" : "+v"(x)); return x; }
; #define SB_LOAD(kt_) do { const size_t m_ = (size_t)b * SEQ + 64 * (kt_) + kr; const bf16* kp_ = Kb + m_ * 2048 + h * 128 + 8 * kp8; const bf16* vp_ = Vb + m_ * 2048 + h * 128 + 8 * kp8; \
;         pk1 = *(const u32x4*)kp_; pk2_ = *(const u32x4*)(kp_ + 64); pv1 = *(const u32x4*)vp_; pv2 = *(const u32x4*)(vp_ + 64); } while (0)
; DI void sb_phase(LAS unsigned char* lds, const bf16* Q, const bf16* Kb, const bf16* Vb, const bf16* Gb, bf16* Y, const float* qg, const float* kg, int G, int blk) {
;     const int tid = launder((int)threadIdx.x), lane = tid & 63, wid = __builtin_amdgcn_readfirstlane(tid >> 6);
;     const int r = lane & 31, hh = lane >> 5, q4 = (lane & 15) >> 2, p4 = lane & 3, blk16 = (lane >> 4) & 1;
;     volatile LAS unsigned* alive = (volatile LAS unsigned*)(lds + LDS_BYTES - 64) + 4;
;     constexpr int KP = 272, TB = 64 * KP, VPs = 320, TBV = 64 * VPs;
;     const int kr = tid >> 3, kp8 = tid & 7;
;     for (int bh = blk; bh < 256; bh += G) {
;         u32x4 pk1, pk2_, pv1, pv2;
;         bf16x8 Qf[8];
;     ...
;             const int b = bh >> 4, h = bh & 15, q0 = 256 * qb;
;             const int r_l = launder(r), hh_l = launder(hh), lane_l = launder(lane);
;             if (qb == 7) {
;                 const bf16* qp = Q + ((size_t)b * SEQ + q0 + 32 * wid + r_l) * 2048 + h * 128 + 8 * hh_l;
; #pragma unroll
;                 for (int s = 0; s < 8; ++s) Qf[s] = *(const bf16x8*)(qp + 16 * s);
;             }
;             f32x16 O[4];
; #pragma unroll
;             for (int d = 0; d < 4; ++d)
; #pragma unroll
;                 for (int i = 0; i < 16; ++i) O[d][i] = 0.f;
;             float R = 1.f;
;             const int ktmax = 4 * qb + 3, stmax = 8 * qb + wid;
;     ...
;             if (qb == 7) SB_LOAD(ktmax);
;             SB_STORE(0);
;             if (tid < 3) alive[tid] = 0u;
;             __syncthreads();
;             int cur = 0;
;             bool wdone = false;
;     ...
;                 if (kt < ktmax && alive[(kt + 1) % 3] == 0u) break;
;                 if (tid == 0) alive[(kt + 2) % 3] = 0u;
;                 if (kt > 0) SB_LOAD(kt - 1);
;                 const LAS unsigned char* Kimg = lds + cur * TB; const LAS unsigned char* Vimg = lds + 2 * TB + cur * TBV;
.LBB0_1068:
	v_mov_b32_e32 v2, v196
	s_cmpk_gt_i32 s89, 0xff
	s_waitcnt vmcnt(0) lgkmcnt(0)
	s_barrier
	s_nop 0
	v_readfirstlane_b32 s0, v2
	s_cbranch_scc1 .LBB0_1106
	v_ashrrev_i32_e32 v146, 3, v2
	v_ashrrev_i32_e32 v147, 31, v146
	s_ashr_i32 s0, s0, 6
	s_cmp_lt_u32 s0, 4
	s_cbranch_scc1 .Lsb_prio_done
	s_setprio 1
.Lsb_prio_done:
	v_and_b32_e32 v3, 7, v2
	v_lshlrev_b64 v[0:1], 11, v[146:147]
	s_mov_b64 s[2:3], 0x3e0000
	s_movk_i32 s81, 0x110
	s_lshl_b32 s77, s0, 5
	v_lshl_add_u64 v[148:149], v[0:1], 0, s[2:3]
	v_mul_lo_u32 v6, v146, s81
	v_lshlrev_b32_e32 v0, 4, v3
	v_and_b32_e32 v151, 63, v2
	s_add_i32 s1, s77, 0x700
	v_add3_u32 v150, 0, v6, v0
	s_mov_b32 s84, s1
	s_ashr_i32 s85, s1, 31
	v_mad_u64_u32 v[152:153], s[2:3], v146, 48, v[150:151]
	s_add_i32 s1, 0, 0x23fd0
	v_readlane_b32 s6, v254, 61
	v_and_b32_e32 v172, 31, v2
	v_bfe_u32 v173, v2, 5, 1
	v_lshrrev_b32_e32 v5, 2, v2
	v_lshlrev_b32_e32 v4, 3, v3
	v_mov_b32_e32 v1, 0
	v_cmp_gt_i32_e64 s[2:3], 3, v2
	v_lshl_add_u32 v153, v2, 2, s1
	v_cmp_eq_u32_e64 s[4:5], 0, v2
	v_readlane_b32 s7, v254, 62
	v_lshlrev_b32_e32 v3, 1, v2
	v_lshlrev_b32_e32 v2, 3, v2
	v_lshl_add_u64 v[154:155], s[6:7], 0, v[0:1]
	v_lshl_add_u64 v[156:157], s[60:61], 0, v[0:1]
	v_lshlrev_b32_e32 v0, 2, v173
	v_and_b32_e32 v2, 24, v2
	v_and_or_b32 v176, v3, 32, v2
	v_or_b32_e32 v3, 1, v0
	v_cmp_lt_u32_e64 s[12:13], v3, v172
	v_or_b32_e32 v3, 2, v0
	v_cmp_lt_u32_e64 s[14:15], v3, v172
	v_or_b32_e32 v3, 3, v0
	v_cmp_lt_u32_e64 s[16:17], v3, v172
	v_or_b32_e32 v3, 8, v0
	v_cmp_lt_u32_e64 s[18:19], v3, v172
	v_or_b32_e32 v3, 9, v0
	v_cmp_lt_u32_e64 s[20:21], v3, v172
	v_or_b32_e32 v3, 10, v0
	v_cmp_lt_u32_e64 s[22:23], v3, v172
	v_or_b32_e32 v3, 11, v0
	v_writelane_b32 v255, s72, 1
	v_cmp_lt_u32_e64 s[24:25], v3, v172
	v_or_b32_e32 v3, 16, v0
	v_writelane_b32 v255, s73, 2
	v_cmp_lt_u32_e64 s[26:27], v3, v172
	v_or_b32_e32 v3, 17, v0
	v_writelane_b32 v255, s48, 3
	v_cmp_lt_u32_e64 s[28:29], v3, v172
	v_or_b32_e32 v3, 18, v0
	v_writelane_b32 v255, s49, 4
	v_cmp_lt_u32_e64 s[30:31], v3, v172
	v_or_b32_e32 v3, 19, v0
	v_writelane_b32 v255, s97, 5
	s_add_i32 s1, s77, 0xffffff00
	v_cmp_lt_u32_e64 s[34:35], v3, v172
	v_or_b32_e32 v3, 24, v0
	v_writelane_b32 v255, s90, 6
	s_mov_b32 s86, s1
	s_ashr_i32 s87, s1, 31
	s_mul_i32 s1, s0, 0x2200
	v_cmp_lt_u32_e64 s[36:37], v3, v172
	v_or_b32_e32 v3, 25, v0
	v_writelane_b32 v255, s91, 7
	v_and_or_b32 v2, v5, 3, v0
	s_add_i32 s90, s1, 0
	s_ashr_i32 s1, s77, 31
	v_cmp_lt_u32_e64 s[10:11], v0, v172
	v_cmp_lt_u32_e64 s[38:39], v3, v172
	v_or_b32_e32 v3, 26, v0
	v_or_b32_e32 v0, 27, v0
	v_mul_u32_u24_e32 v177, 0x140, v2
	s_add_i32 s90, s90, 0x12800
	v_writelane_b32 v254, s1, 4
	v_lshlrev_b32_e32 v2, 1, v172
	v_cmp_lt_u32_e64 s[42:43], v0, v172
	v_mul_u32_u24_e32 v0, 0x440, v173
	s_mov_b32 s47, 0
	v_mul_u32_u24_e32 v174, 0x110, v172
	v_lshlrev_b32_e32 v175, 4, v173
	v_cmp_gt_u32_e64 s[6:7], 32, v151
	v_cmp_ne_u32_e64 s[8:9], 0, v151
	v_cmp_lt_u32_e64 s[40:41], v3, v172
	v_add3_u32 v178, s90, v2, v0
	s_add_i32 s76, s0, -6
	s_add_i32 s1, s0, -7
	v_lshlrev_b32_e32 v158, 1, v4
	v_mov_b32_e32 v159, v1
	v_mov_b32_e32 v179, 1
	s_movk_i32 s62, 0x4000
	s_mov_b32 s63, 0x8000
	s_mov_b32 s54, 0xc000
	s_mov_b32 s55, 0x10000
	s_mov_b32 s56, 0x14000
	s_mov_b32 s57, 0x18000
	v_mov_b32_e32 v180, 0xf149f2ca
	v_writelane_b32 v254, s89, 34
	s_mov_b32 s33, s89
	s_branch .LBB0_1071

; __device__ __forceinline__ unsigned xb_ld(unsigned* p)              { return __hip_atomic_load(p, __ATOMIC_RELAXED, __HIP_MEMORY_SCOPE_AGENT); }
; __device__ __forceinline__ void xcd_barrier_complete(unsigned* bar, unsigned x, unsigned& nloc, unsigned& nx) {
;     const unsigned G = gridDim.x * gridDim.y * gridDim.z;
;     unsigned sum, cnt, mine, sp = 0u;
;     for (;;) {
;         sum = 0u; cnt = 0u; mine = 0u;
; #pragma unroll
;         for (unsigned j = 0; j < 16; ++j) { const unsigned c = xb_ld(&bar[XB_XCNT(j)]); sum += c; cnt += (c > 0u) ? 1u : 0u; mine = (j == x) ? c : mine; }
; __device__ __forceinline__ void xcd_barrier(const XcdBarrier& b) {
;     asm volatile("s_waitcnt vmcnt(0)" ::: "memory");
;     __syncthreads();
;     if (threadIdx.x == 0) {
;         unsigned* bar = b.bar;
;         __builtin_amdgcn_s_waitcnt(0);
;         unsigned nloc = b.st[0], nx = b.st[1];
;         if (nloc == 0u) { xcd_barrier_complete(bar, b.x, nloc, nx); b.st[0] = nloc; b.st[1] = nx; }
.LBB0_1106:
	s_setprio 0
	s_cmp_gt_i32 s91, 12
	s_cselect_b64 s[2:3], -1, 0
	s_and_b64 s[0:1], s[48:49], s[2:3]
	v_readlane_b32 s44, v254, 24
	v_readlane_b32 s56, v254, 63
	s_andn2_b64 vcc, exec, s[0:1]
	v_readlane_b32 s48, v254, 28
	v_readlane_b32 s49, v254, 29
	v_readlane_b32 s50, v254, 30
	v_readlane_b32 s51, v254, 31
	v_readlane_b32 s57, v255, 0
	v_readlane_b32 s45, v254, 25
	v_readlane_b32 s46, v254, 26
	v_readlane_b32 s47, v254, 27
	s_cbranch_vccnz .LBB0_1160
	s_waitcnt vmcnt(0)
	s_waitcnt vmcnt(0) lgkmcnt(0)
	s_barrier
	s_and_saveexec_b64 s[0:1], s[66:67]
	s_cbranch_execz .LBB0_1159
	s_add_i32 s4, 0, 0x23fc0
	v_mov_b32_e32 v0, s4
	s_waitcnt vmcnt(0) expcnt(0) lgkmcnt(0)
	ds_read_b32 v2, v0
	s_add_i32 s4, 0, 0x23fc4
	v_mov_b32_e32 v0, s4
	ds_read_b32 v0, v0
	s_waitcnt lgkmcnt(1)
	v_cmp_ne_u32_e32 vcc, 0, v2
	s_cbranch_vccnz .LBB0_1123
	v_readlane_b32 s4, v254, 0
	v_readlane_b32 s5, v254, 1
	s_load_dwordx2 s[8:9], s[4:5], 0x4
	s_add_u32 s4, s50, 0x1000
	s_addc_u32 s5, s51, 0
	s_add_u32 s6, s50, 0x1100
	s_addc_u32 s7, s51, 0
	s_waitcnt lgkmcnt(0)
	s_mul_i32 s18, s8, s88
	s_add_u32 s8, s50, 0x1200
	s_mul_i32 s18, s18, s9
	s_addc_u32 s9, s51, 0
	s_add_u32 s10, s50, 0x1300
	s_addc_u32 s11, s51, 0
	s_mov_b32 s19, 1
	v_mov_b32_e32 v16, 0
	s_branch .LBB0_1111
